# E_BF16 GEMM epilogue: v_permlane16_swap pairs -> 16 global_store_dwordx4 per lane instead of 32 dwordx2 (same bytes, same addresses)
# speedup vs baseline: 1.0128x; 1.0084x over previous
.LBB0_1284:
	s_and_b64 vcc, exec, s[2:3]
	s_cbranch_vccz .LBB0_632
	v_subrev_u32_e32 v0, s39, v0
	v_ashrrev_i32_e32 v131, 31, v130
	v_ashrrev_i32_e32 v132, 31, v0
	v_mul_lo_u32 v134, v132, s46
	v_mad_u64_u32 v[132:133], s[2:3], v0, s46, 0
	v_add_u32_e32 v133, v133, v134
	v_lshl_add_u64 v[132:133], v[132:133], 1, s[42:43]
	v_lshlrev_b64 v[130:131], 1, v[130:131]
	v_lshl_add_u64 v[132:133], v[132:133], 0, v[130:131]
	v_and_b32_e32 v134, 1, v223
	v_mul_u32_u24_e32 v134, 24, v134
	v_mov_b32_e32 v135, 0
	v_lshl_add_u64 v[132:133], v[132:133], 0, v[134:135]
	s_lshl_b32 s4, s46, 5
	s_mov_b32 s5, 0
	v_cvt_pk_bf16_f32 v126, v126, v127
	v_cvt_pk_bf16_f32 v127, v128, v129
	v_cvt_pk_bf16_f32 v128, v122, v123
	v_cvt_pk_bf16_f32 v129, v124, v125
	s_nop 1
	v_permlane16_swap_b32_e32 v126, v128
	v_permlane16_swap_b32_e32 v127, v129
	global_store_dwordx4 v[132:133], v[126:129], off
	v_cvt_pk_bf16_f32 v118, v118, v119
	v_cvt_pk_bf16_f32 v119, v120, v121
	v_cvt_pk_bf16_f32 v120, v114, v115
	v_cvt_pk_bf16_f32 v121, v116, v117
	s_nop 1
	v_permlane16_swap_b32_e32 v118, v120
	v_permlane16_swap_b32_e32 v119, v121
	global_store_dwordx4 v[132:133], v[118:121], off offset:64
	v_lshl_add_u64 v[132:133], v[132:133], 0, s[4:5]
	v_cvt_pk_bf16_f32 v110, v110, v111
	v_cvt_pk_bf16_f32 v111, v112, v113
	v_cvt_pk_bf16_f32 v112, v106, v107
	v_cvt_pk_bf16_f32 v113, v108, v109
	s_nop 1
	v_permlane16_swap_b32_e32 v110, v112
	v_permlane16_swap_b32_e32 v111, v113
	global_store_dwordx4 v[132:133], v[110:113], off
	v_cvt_pk_bf16_f32 v102, v102, v103
	v_cvt_pk_bf16_f32 v103, v104, v105
	v_cvt_pk_bf16_f32 v104, v98, v99
	v_cvt_pk_bf16_f32 v105, v100, v101
	s_nop 1
	v_permlane16_swap_b32_e32 v102, v104
	v_permlane16_swap_b32_e32 v103, v105
	global_store_dwordx4 v[132:133], v[102:105], off offset:64
	v_lshl_add_u64 v[132:133], v[132:133], 0, s[4:5]
	v_cvt_pk_bf16_f32 v94, v94, v95
	v_cvt_pk_bf16_f32 v95, v96, v97
	v_cvt_pk_bf16_f32 v96, v90, v91
	v_cvt_pk_bf16_f32 v97, v92, v93
	s_nop 1
	v_permlane16_swap_b32_e32 v94, v96
	v_permlane16_swap_b32_e32 v95, v97
	global_store_dwordx4 v[132:133], v[94:97], off
	v_cvt_pk_bf16_f32 v86, v86, v87
	v_cvt_pk_bf16_f32 v87, v88, v89
	v_cvt_pk_bf16_f32 v88, v82, v83
	v_cvt_pk_bf16_f32 v89, v84, v85
	s_nop 1
	v_permlane16_swap_b32_e32 v86, v88
	v_permlane16_swap_b32_e32 v87, v89
	global_store_dwordx4 v[132:133], v[86:89], off offset:64
	v_lshl_add_u64 v[132:133], v[132:133], 0, s[4:5]
	v_cvt_pk_bf16_f32 v78, v78, v79
	v_cvt_pk_bf16_f32 v79, v80, v81
	v_cvt_pk_bf16_f32 v80, v74, v75
	v_cvt_pk_bf16_f32 v81, v76, v77
	s_nop 1
	v_permlane16_swap_b32_e32 v78, v80
	v_permlane16_swap_b32_e32 v79, v81
	global_store_dwordx4 v[132:133], v[78:81], off
	v_cvt_pk_bf16_f32 v70, v70, v71
	v_cvt_pk_bf16_f32 v71, v72, v73
	v_cvt_pk_bf16_f32 v72, v66, v67
	v_cvt_pk_bf16_f32 v73, v68, v69
	s_nop 1
	v_permlane16_swap_b32_e32 v70, v72
	v_permlane16_swap_b32_e32 v71, v73
	global_store_dwordx4 v[132:133], v[70:73], off offset:64
	v_lshl_add_u64 v[132:133], v[132:133], 0, s[4:5]
	v_cvt_pk_bf16_f32 v62, v62, v63
	v_cvt_pk_bf16_f32 v63, v64, v65
	v_cvt_pk_bf16_f32 v64, v58, v59
	v_cvt_pk_bf16_f32 v65, v60, v61
	s_nop 1
	v_permlane16_swap_b32_e32 v62, v64
	v_permlane16_swap_b32_e32 v63, v65
	global_store_dwordx4 v[132:133], v[62:65], off
	v_cvt_pk_bf16_f32 v54, v54, v55
	v_cvt_pk_bf16_f32 v55, v56, v57
	v_cvt_pk_bf16_f32 v56, v50, v51
	v_cvt_pk_bf16_f32 v57, v52, v53
	s_nop 1
	v_permlane16_swap_b32_e32 v54, v56
	v_permlane16_swap_b32_e32 v55, v57
	global_store_dwordx4 v[132:133], v[54:57], off offset:64
	v_lshl_add_u64 v[132:133], v[132:133], 0, s[4:5]
	v_cvt_pk_bf16_f32 v46, v46, v47
	v_cvt_pk_bf16_f32 v47, v48, v49
	v_cvt_pk_bf16_f32 v48, v42, v43
	v_cvt_pk_bf16_f32 v49, v44, v45
	s_nop 1
	v_permlane16_swap_b32_e32 v46, v48
	v_permlane16_swap_b32_e32 v47, v49
	global_store_dwordx4 v[132:133], v[46:49], off
	v_cvt_pk_bf16_f32 v34, v34, v35
	v_cvt_pk_bf16_f32 v35, v36, v37
	v_cvt_pk_bf16_f32 v36, v30, v31
	v_cvt_pk_bf16_f32 v37, v32, v33
	s_nop 1
	v_permlane16_swap_b32_e32 v34, v36
	v_permlane16_swap_b32_e32 v35, v37
	global_store_dwordx4 v[132:133], v[34:37], off offset:64
	v_lshl_add_u64 v[132:133], v[132:133], 0, s[4:5]
	v_cvt_pk_bf16_f32 v38, v38, v39
	v_cvt_pk_bf16_f32 v39, v40, v41
	v_cvt_pk_bf16_f32 v40, v26, v27
	v_cvt_pk_bf16_f32 v41, v28, v29
	s_nop 1
	v_permlane16_swap_b32_e32 v38, v40
	v_permlane16_swap_b32_e32 v39, v41
	global_store_dwordx4 v[132:133], v[38:41], off
	v_cvt_pk_bf16_f32 v22, v22, v23
	v_cvt_pk_bf16_f32 v23, v24, v25
	v_cvt_pk_bf16_f32 v24, v18, v19
	v_cvt_pk_bf16_f32 v25, v20, v21
	s_nop 1
	v_permlane16_swap_b32_e32 v22, v24
	v_permlane16_swap_b32_e32 v23, v25
	global_store_dwordx4 v[132:133], v[22:25], off offset:64
	v_lshl_add_u64 v[132:133], v[132:133], 0, s[4:5]
	v_cvt_pk_bf16_f32 v14, v14, v15
	v_cvt_pk_bf16_f32 v15, v16, v17
	v_cvt_pk_bf16_f32 v16, v10, v11
	v_cvt_pk_bf16_f32 v17, v12, v13
	s_nop 1
	v_permlane16_swap_b32_e32 v14, v16
	v_permlane16_swap_b32_e32 v15, v17
	global_store_dwordx4 v[132:133], v[14:17], off
	v_cvt_pk_bf16_f32 v6, v6, v7
	v_cvt_pk_bf16_f32 v7, v8, v9
	v_cvt_pk_bf16_f32 v8, v2, v3
	v_cvt_pk_bf16_f32 v9, v4, v5
	s_nop 1
	v_permlane16_swap_b32_e32 v6, v8
	v_permlane16_swap_b32_e32 v7, v9
	global_store_dwordx4 v[132:133], v[6:9], off offset:64
	s_branch .LBB0_632
